# sample attention loop back edge rotated: next iteration's K fragment LDS reads issued right after the loop-back barrier (before the two trailing PV MFMAs)
# speedup vs baseline: 1.0054x; 1.0054x over previous
.LBB0_374:
	s_andn2_saveexec_b64 s[0:1], s[0:1]
	v_lshlrev_b64 v[0:1], 10, v[2:3]
	v_lshl_add_u64 v[0:1], s[2:3], 0, v[0:1]
	v_mov_b32_e32 v13, v137
	v_lshl_add_u64 v[0:1], v[0:1], 0, v[12:13]
	s_or_b64 exec, exec, s[0:1]
	s_ashr_i32 s71, s70, 31
	s_lshl_b64 s[0:1], s[70:71], 1
	v_readlane_b32 s4, v252, 63
	v_readlane_b32 s5, v253, 0
	s_add_u32 s0, s4, s0
	s_addc_u32 s1, s5, s1
	v_mov_b32_e32 v15, v137
	global_load_dwordx4 v[104:107], v[0:1], off
	v_lshl_add_u64 v[0:1], s[0:1], 0, v[14:15]
	v_lshl_add_u64 v[2:3], v[0:1], 0, v[136:137]
	v_mov_b32_e32 v121, v137
	v_lshl_add_u64 v[0:1], v[0:1], 0, v[120:121]
	global_load_dwordx4 v[108:111], v[2:3], off
	global_load_dwordx4 v[112:115], v[0:1], off
	v_lshl_add_u64 v[122:123], s[4:5], 0, v[14:15]
	v_readlane_b32 s4, v253, 3
	s_add_i32 s0, s22, 0x2080
	v_mov_b32_e32 v9, v137
	v_readlane_b32 s5, v253, 4
	v_mov_b32_e32 v11, v137
	v_mov_b32_e32 v13, v137
	v_mov_b32_e32 v14, v137
	v_lshlrev_b32_e32 v118, 3, v19
	v_mul_u32_u24_e32 v152, 0x90, v16
	v_mul_u32_u24_e32 v153, 0x90, v17
	v_lshl_add_u32 v154, v19, 4, s24
	v_lshl_add_u64 v[124:125], s[4:5], 0, v[8:9]
	v_lshl_add_u64 v[126:127], s[2:3], 0, v[8:9]
	v_lshl_add_u64 v[128:129], s[4:5], 0, v[10:11]
	v_lshl_add_u64 v[130:131], s[2:3], 0, v[10:11]
	v_lshl_add_u64 v[132:133], s[4:5], 0, v[12:13]
	v_lshl_add_u64 v[134:135], s[2:3], 0, v[12:13]
	v_mul_u32_u24_e32 v155, 0xd0, v18
	v_mul_u32_u24_e32 v142, 0x90, v18
	v_add_u32_sdwa v156, s0, v22 dst_sel:DWORD dst_unused:UNUSED_PAD src0_sel:DWORD src1_sel:WORD_1
	v_add_u32_sdwa v157, s0, v21 dst_sel:DWORD dst_unused:UNUSED_PAD src0_sel:DWORD src1_sel:WORD_1
	v_add_u32_e32 v158, s0, v20
	v_mov_b32_e32 v0, v137
	v_mov_b32_e32 v1, v137
	v_mov_b32_e32 v2, v137
	v_mov_b32_e32 v3, v137
	v_mov_b32_e32 v4, v137
	v_mov_b32_e32 v5, v137
	v_mov_b32_e32 v6, v137
	v_mov_b32_e32 v7, v137
	v_mov_b32_e32 v8, v137
	v_mov_b32_e32 v10, v137
	v_mov_b32_e32 v12, v137
	v_mov_b64_e32 v[30:31], v[14:15]
	v_add_u32_e32 v143, s24, v118
	s_mov_b32 s1, 0
	v_mov_b32_e32 v151, 0xf149f2ca
	v_mov_b32_e32 v119, 0
	v_mov_b64_e32 v[28:29], v[12:13]
	v_mov_b64_e32 v[26:27], v[10:11]
	v_mov_b64_e32 v[24:25], v[8:9]
	v_mov_b64_e32 v[22:23], v[6:7]
	v_mov_b64_e32 v[20:21], v[4:5]
	v_mov_b64_e32 v[18:19], v[2:3]
	v_mov_b64_e32 v[16:17], v[0:1]
	s_mov_b32 s3, 0
	s_movk_i32 s4, 0xff80
	s_mov_b32 s5, -1
	v_mov_b32_e32 v238, 0x1000
	v_mov_b32_e32 v239, 0x10000
	v_add_u32_e32 v32, s1, v158
	v_ashrrev_i32_e32 v33, 31, v32
	v_lshlrev_b64 v[34:35], 10, v[32:33]
	v_lshlrev_b64 v[32:33], 6, v[32:33]
	v_lshl_add_u64 v[32:33], v[124:125], 0, v[32:33]
	v_lshl_add_u64 v[34:35], v[126:127], 0, v[34:35]
	v_lshl_add_u64 v[32:33], v[32:33], 0, s[4:5]
	v_cndmask_b32_e64 v241, v33, v35, s[40:41]
	v_cndmask_b32_e64 v240, v32, v34, s[40:41]
	v_add_u32_e32 v32, s1, v157
	v_ashrrev_i32_e32 v33, 31, v32
	v_lshlrev_b64 v[34:35], 10, v[32:33]
	v_lshlrev_b64 v[32:33], 6, v[32:33]
	v_lshl_add_u64 v[32:33], v[128:129], 0, v[32:33]
	v_lshl_add_u64 v[34:35], v[130:131], 0, v[34:35]
	v_lshl_add_u64 v[32:33], v[32:33], 0, s[4:5]
	v_cndmask_b32_e64 v243, v33, v35, s[42:43]
	v_cndmask_b32_e64 v242, v32, v34, s[42:43]
	v_add_u32_e32 v32, s1, v156
	v_ashrrev_i32_e32 v33, 31, v32
	v_lshlrev_b64 v[34:35], 10, v[32:33]
	v_lshlrev_b64 v[32:33], 6, v[32:33]
	v_lshl_add_u64 v[32:33], v[132:133], 0, v[32:33]
	v_lshl_add_u64 v[34:35], v[134:135], 0, v[34:35]
	v_lshl_add_u64 v[32:33], v[32:33], 0, s[4:5]
	v_cndmask_b32_e64 v245, v33, v35, s[44:45]
	v_cndmask_b32_e64 v244, v32, v34, s[44:45]
	s_add_i32 s22, s0, s1
	s_ashr_i32 s23, s22, 31
	v_lshl_add_u64 v[32:33], s[22:23], 1, v[122:123]
	v_lshl_add_u64 v[246:247], v[32:33], 0, v[136:137]
	v_mov_b32_e32 v121, v137
	v_lshl_add_u64 v[248:249], v[32:33], 0, v[120:121]
	v_mov_b32_e32 v120, 0
	v_mov_b32_e32 v121, 0
	v_mov_b32_e32 v122, 0
	v_mov_b32_e32 v123, 0
	v_mov_b32_e32 v124, 0
	v_mov_b32_e32 v125, 0
	v_mov_b32_e32 v126, 0
	v_mov_b32_e32 v127, 0
	v_mov_b32_e32 v128, 0
	v_mov_b32_e32 v129, 0
	v_mov_b32_e32 v130, 0
	v_mov_b32_e32 v131, 0
	v_mov_b32_e32 v132, 0
	v_mov_b32_e32 v133, 0
	v_mov_b32_e32 v134, 0
	v_mov_b32_e32 v135, 0
	s_waitcnt lgkmcnt(0)
	s_barrier
	v_readfirstlane_b32 s22, v139
	s_bitcmp1_b32 s22, 8
	s_cbranch_scc0 .Lsa_no_e1
	s_barrier
.Lsa_no_e1:
	s_and_b32 s22, s3, 1
	s_mul_i32 s22, s22, 0x3400
	v_add3_u32 v160, v154, s22, v155
	ds_read_b128 v[190:193], v160
	ds_read_b128 v[194:197], v160 offset:32
	ds_read_b128 v[198:201], v160 offset:64
	ds_read_b128 v[202:205], v160 offset:96
	ds_read_b128 v[206:209], v160 offset:128
	ds_read_b128 v[210:213], v160 offset:160
	ds_read_b128 v[214:217], v160 offset:6656
	ds_read_b128 v[218:221], v160 offset:6688
	ds_read_b128 v[222:225], v160 offset:6720
	ds_read_b128 v[226:229], v160 offset:6752
	ds_read_b128 v[230:233], v160 offset:6784
	ds_read_b128 v[234:237], v160 offset:6816
.LBB0_377:
	s_add_i32 s2, s3, 1
	s_bitcmp1_b32 s2, 0
	s_cselect_b32 s22, 0x3400, 0
	s_cselect_b32 s23, 0x2400, 0
	s_add_i32 s22, s24, s22
	s_and_b32 s3, s3, 1
	s_cmpk_lg_i32 s1, 0x200
	s_cbranch_scc1 .Lsa_noq
	v_mov_b32_e32 v67, v95
	v_mov_b32_e32 v66, v94
	v_mov_b32_e32 v65, v93
	v_mov_b32_e32 v64, v92
	v_mov_b32_e32 v71, v91
	v_mov_b32_e32 v70, v90
	v_mov_b32_e32 v69, v89
	v_mov_b32_e32 v68, v88

.LBB0_381:
	s_barrier
	s_mulk_i32 s3, 0x2400
	v_add3_u32 v190, v143, s3, v142
	v_add_u32_e32 v191, 0x6800, v190
	v_add_u32_e32 v192, 0x7a00, v190
	ds_read2_b64 v[194:197], v191 offset1:2
	ds_read2_b64 v[198:201], v192 offset1:2
	ds_read2_b64 v[202:205], v191 offset0:4 offset1:6
	ds_read2_b64 v[206:209], v192 offset0:4 offset1:6
	ds_read2_b64 v[210:213], v191 offset0:8 offset1:10
	ds_read2_b64 v[214:217], v192 offset0:8 offset1:10
	ds_read2_b64 v[218:221], v191 offset0:12 offset1:14
	ds_read2_b64 v[222:225], v192 offset0:12 offset1:14
	v_exp_f32_e32 v32, v32
	v_exp_f32_e32 v33, v33
	v_exp_f32_e32 v34, v34
	v_exp_f32_e32 v35, v35
	v_exp_f32_e32 v36, v36
	v_exp_f32_e32 v37, v37
	v_exp_f32_e32 v38, v38
	v_exp_f32_e32 v39, v39
	v_cvt_pk_bf16_f32 v160, v32, v33
	v_cvt_pk_bf16_f32 v161, v34, v35
	v_cvt_pk_bf16_f32 v162, v36, v37
	v_cvt_pk_bf16_f32 v163, v38, v39
	v_add_f32_e32 v168, v32, v33
	v_add_f32_e32 v169, v34, v35
	v_add_f32_e32 v168, v168, v36
	v_add_f32_e32 v169, v169, v37
	v_add_f32_e32 v168, v168, v38
	v_add_f32_e32 v169, v169, v39
	s_waitcnt lgkmcnt(6)
	v_mfma_f32_32x32x16_bf16 v[16:31], v[194:197], v[160:163], v[16:31]
	v_mfma_f32_32x32x16_bf16 v[0:15], v[198:201], v[160:163], v[0:15]
	v_exp_f32_e32 v40, v40
	v_exp_f32_e32 v41, v41
	v_exp_f32_e32 v42, v42
	v_exp_f32_e32 v43, v43
	v_exp_f32_e32 v44, v44
	v_exp_f32_e32 v45, v45
	v_exp_f32_e32 v46, v46
	v_exp_f32_e32 v47, v47
	v_cvt_pk_bf16_f32 v164, v40, v41
	v_cvt_pk_bf16_f32 v165, v42, v43
	v_cvt_pk_bf16_f32 v166, v44, v45
	v_cvt_pk_bf16_f32 v167, v46, v47
	v_add_f32_e32 v168, v168, v40
	v_add_f32_e32 v169, v169, v41
	v_add_f32_e32 v168, v168, v42
	v_add_f32_e32 v169, v169, v43
	v_add_f32_e32 v168, v168, v44
	v_add_f32_e32 v169, v169, v45
	v_add_f32_e32 v168, v168, v46
	v_add_f32_e32 v169, v169, v47
	s_waitcnt lgkmcnt(4)
	v_mfma_f32_32x32x16_bf16 v[16:31], v[202:205], v[164:167], v[16:31]
	v_mfma_f32_32x32x16_bf16 v[0:15], v[206:209], v[164:167], v[0:15]
	v_exp_f32_e32 v48, v48
	v_exp_f32_e32 v49, v49
	v_exp_f32_e32 v50, v50
	v_exp_f32_e32 v51, v51
	v_exp_f32_e32 v52, v52
	v_exp_f32_e32 v53, v53
	v_exp_f32_e32 v54, v54
	v_exp_f32_e32 v55, v55
	v_cvt_pk_bf16_f32 v160, v48, v49
	v_cvt_pk_bf16_f32 v161, v50, v51
	v_cvt_pk_bf16_f32 v162, v52, v53
	v_cvt_pk_bf16_f32 v163, v54, v55
	v_add_f32_e32 v168, v168, v48
	v_add_f32_e32 v169, v169, v49
	v_add_f32_e32 v168, v168, v50
	v_add_f32_e32 v169, v169, v51
	v_add_f32_e32 v168, v168, v52
	v_add_f32_e32 v169, v169, v53
	v_add_f32_e32 v168, v168, v54
	v_add_f32_e32 v169, v169, v55
	s_waitcnt lgkmcnt(2)
	v_mfma_f32_32x32x16_bf16 v[16:31], v[210:213], v[160:163], v[16:31]
	v_mfma_f32_32x32x16_bf16 v[0:15], v[214:217], v[160:163], v[0:15]
	v_exp_f32_e32 v56, v56
	v_exp_f32_e32 v57, v57
	v_exp_f32_e32 v58, v58
	v_exp_f32_e32 v59, v59
	v_exp_f32_e32 v60, v60
	v_exp_f32_e32 v61, v61
	v_exp_f32_e32 v62, v62
	v_exp_f32_e32 v63, v63
	v_cvt_pk_bf16_f32 v164, v56, v57
	v_cvt_pk_bf16_f32 v165, v58, v59
	v_cvt_pk_bf16_f32 v166, v60, v61
	v_cvt_pk_bf16_f32 v167, v62, v63
	v_add_f32_e32 v168, v168, v56
	v_add_f32_e32 v169, v169, v57
	v_add_f32_e32 v168, v168, v58
	v_add_f32_e32 v169, v169, v59
	v_add_f32_e32 v168, v168, v60
	v_add_f32_e32 v169, v169, v61
	v_add_f32_e32 v168, v168, v62
	v_add_f32_e32 v169, v169, v63
	v_add_f32_e32 v168, v168, v169
	v_add_f32_e32 v119, v119, v168
	s_and_b32 s22, s2, 1
	s_mul_i32 s22, s22, 0x3400
	v_add3_u32 v160, v154, s22, v155
	s_add_i32 s1, s1, 64
	s_cmpk_lg_i32 s1, 0x11c0
	s_waitcnt lgkmcnt(0)
	s_barrier
	ds_read_b128 v[190:193], v160
	ds_read_b128 v[194:197], v160 offset:32
	ds_read_b128 v[198:201], v160 offset:64
	ds_read_b128 v[202:205], v160 offset:96
	ds_read_b128 v[206:209], v160 offset:128
	ds_read_b128 v[210:213], v160 offset:160
	ds_read_b128 v[214:217], v160 offset:6656
	ds_read_b128 v[226:229], v160 offset:6752
	ds_read_b128 v[230:233], v160 offset:6784
	ds_read_b128 v[234:237], v160 offset:6816
	v_mfma_f32_32x32x16_bf16 v[16:31], v[218:221], v[164:167], v[16:31]
	v_mfma_f32_32x32x16_bf16 v[0:15], v[222:225], v[164:167], v[0:15]
	ds_read_b128 v[218:221], v160 offset:6688
	ds_read_b128 v[222:225], v160 offset:6720
	s_cbranch_scc0 .LBB0_383
	s_mov_b32 s3, s2
	s_branch .LBB0_377
